# first grid barrier: the 16 census counter loads issued together (one wait) instead of 16 dependent round trips
# speedup vs baseline: 1.0265x; 1.0016x over previous
.LBB0_113:
	v_readlane_b32 s6, v251, 4
	v_readlane_b32 s7, v251, 5
	global_load_dword v2, v17, s[88:89] sc1
	global_load_dword v1, v17, s[94:95] sc1
	s_mov_b64 s[20:21], -1
	s_mov_b64 s[22:23], -1
	s_nop 1
	global_load_dword v3, v17, s[6:7] sc1
	v_readlane_b32 s6, v251, 6
	v_readlane_b32 s7, v251, 7
	s_nop 4
	global_load_dword v4, v17, s[6:7] sc1
	v_readlane_b32 s6, v251, 8
	v_readlane_b32 s7, v251, 9
	s_nop 4
	global_load_dword v5, v17, s[6:7] sc1
	v_readlane_b32 s6, v251, 10
	v_readlane_b32 s7, v251, 11
	s_nop 4
	global_load_dword v6, v17, s[6:7] sc1
	v_readlane_b32 s6, v251, 12
	v_readlane_b32 s7, v251, 13
	s_nop 4
	global_load_dword v7, v17, s[6:7] sc1
	v_readlane_b32 s6, v251, 14
	v_readlane_b32 s7, v251, 15
	s_nop 4
	global_load_dword v8, v17, s[6:7] sc1
	v_readlane_b32 s6, v251, 16
	v_readlane_b32 s7, v251, 17
	s_nop 4
	global_load_dword v9, v17, s[6:7] sc1
	v_readlane_b32 s6, v251, 18
	v_readlane_b32 s7, v251, 19
	s_nop 4
	global_load_dword v10, v17, s[6:7] sc1
	v_readlane_b32 s6, v251, 20
	v_readlane_b32 s7, v251, 21
	s_nop 4
	global_load_dword v11, v17, s[6:7] sc1
	v_readlane_b32 s6, v251, 22
	v_readlane_b32 s7, v251, 23
	s_nop 4
	global_load_dword v12, v17, s[6:7] sc1
	v_readlane_b32 s6, v251, 24
	v_readlane_b32 s7, v251, 25
	s_nop 4
	global_load_dword v13, v17, s[6:7] sc1
	v_readlane_b32 s6, v251, 26
	v_readlane_b32 s7, v251, 27
	s_nop 4
	global_load_dword v14, v17, s[6:7] sc1
	v_readlane_b32 s6, v251, 28
	v_readlane_b32 s7, v251, 29
	s_nop 4
	global_load_dword v15, v17, s[6:7] sc1
	v_readlane_b32 s6, v251, 30
	v_readlane_b32 s7, v251, 31
	s_nop 4
	global_load_dword v16, v17, s[6:7] sc1
	s_waitcnt vmcnt(0)
	v_add_u32_e32 v18, v1, v2
	v_add_u32_e32 v18, v18, v3
	v_add_u32_e32 v18, v18, v4
	v_add_u32_e32 v18, v18, v5
	v_add_u32_e32 v18, v18, v6
	v_add_u32_e32 v18, v18, v7
	v_add_u32_e32 v18, v18, v8
	v_add_u32_e32 v18, v18, v9
	v_add_u32_e32 v18, v18, v10
	v_add_u32_e32 v18, v18, v11
	v_add_u32_e32 v18, v18, v12
	v_add_u32_e32 v18, v18, v13
	v_add_u32_e32 v18, v18, v14
	v_add_u32_e32 v18, v18, v15
	v_add_u32_e32 v18, v18, v16
	v_cmp_eq_u32_e32 vcc, s4, v18
	s_cbranch_vccnz .LBB0_112
	s_and_b32 s5, s3, 0xff
	s_cmp_eq_u32 s5, 0
	s_mov_b64 s[24:25], -1
	s_sleep 1
	s_cbranch_scc1 .LBB0_117
	s_and_b64 vcc, exec, s[24:25]
	s_cbranch_vccz .LBB0_112
